# hand-written DSA (masked MQA) attention body added on top of the fused differential attention: selection words prefetched per tile from global memory, masked wave-tiles skipped, exp/pack in the P.V ga
# speedup vs baseline: 1.0491x; 1.0001x over previous
;   #define DMA_K(t,slot) glds16(ksrc+(long)(t)*KVBLK*KP,(unsigned)__builtin_amdgcn_readfirstlane(kdst+(slot)))
;   #define DMA_V(t,slot) glds16(vsrc+(long)(t)*KVBLK*VP,(unsigned)__builtin_amdgcn_readfirstlane(vdst+(slot)))
;   int tidv; asm volatile("v_mbcnt_lo_u32_b32 %0, -1, 0\n\tv_mbcnt_hi_u32_b32 %0, -1, %0":"=v"(tidv)); tidv+=wave_*64;
;   const int tid=tidv,lane=tid&63,r32=lane&31,hi=lane>>5; const int wid=__builtin_amdgcn_readfirstlane(tid>>6);
;   const int q0=qb*QB;
;   const bf16*Qw=Qb+(long)(wid*QBLK)*QP;
;   const unsigned lds0=(unsigned)(uintptr_t)shm;
;   float*wsf=(float*)(shm+LDS_WS)+wid*64;
;   const bf16*ksrc=Kh+(long)lane*KP+wid*8;
;   const bf16*vsrc=Vh+(long)(16*(wid&3)+(lane>>2))*VP+(wid>>2)*32+(lane&3)*8;
;   const unsigned kdst=lds0+LDS_K+wid*1024, vdst=lds0+LDS_V+wid*1024;
;     ...
;   const int vb0=(int)(lds0+LDS_V)+((lane>>4)&1)*32+(lane&3)*8+(4*hi+((lane&15)>>2))*64;
;   const char*Kbase=shm+LDS_K; bf16x8 kf[8];
;   const lds_cptr shm3=(lds_cptr)shm; const lds_cptr kp0=shm3+LDS_K+hi*1024+r32*16; const lds_cptr vp0=shm3+LDS_V+((lane>>4)&1)*32+(lane&3)*8+(4*hi+((lane&15)>>2))*64;
;   const int NT=(q0+QB)/KVBLK;
;   const __attribute__((address_space(3))) unsigned* mimg=(const __attribute__((address_space(3))) unsigned*)(shm3+LDS_OST+wid*MWAVE)+r32;
;   DMA_K(0,0);DMA_V(0,0);DMA_K(1,SLOTB);
;   if constexpr(MASKED){
;     __attribute__((address_space(3))) u32x4* mdst=(__attribute__((address_space(3))) u32x4*)(shm3+LDS_OST+wid*MWAVE)+lane;
;     for(int i=0;i<=qb;++i){ const u32x4 v=((const u32x4*)mwave)[i*64+lane]; mdst[i*64]=v; }
;   }
;   bf16x8 qr[4];
;   #pragma unroll
;   for(int d0=0;d0<4;++d0)qr[d0]=*reinterpret_cast<const bf16x8*>(&Qw[(long)r32*QP+d0*16+hi*8]);
;   float mhat=0.f,l_reg=0.f;f32x16 o[2];o[0]=f32x16{};o[1]=f32x16{};f32x16 negm=f32x16{};asm volatile("":"+v"(negm));
;   const int qrel=wid*QBLK+r32;
; __device__ __forceinline__ void run(Frame& F, int qword) {
;     ...
;             attn_body::attn_unit<8, true>(qb, QA + rq * 512 + h * 64, 512, KA + r0 * 64, 64, VA + r0 * 64, 64, ATT + rq * 1024 + h * 64, 1024,
;                                           MASK + (size_t)(b * 64 + qb * 8 + F.wave) * 2048, shm, F.wave);
.Lds_entry:
	v_readlane_b32 s8, v254, 11
	v_mbcnt_lo_u32_b32 v0, -1, 0
	v_mbcnt_hi_u32_b32 v0, -1, v0
	v_and_b32_e32 v2, 31, v0
	v_lshrrev_b32_e32 v3, 5, v0
	s_lshl_b32 s89, s79, 2
	s_add_i32 s89, s89, 4
	s_lshl_b32 s0, s8, 4
	v_lshlrev_b32_e32 v10, 7, v0
	v_add_u32_e32 v10, s0, v10
	s_and_b32 s0, s8, 3
	s_lshl_b32 s0, s0, 11
	s_lshr_b32 s1, s8, 2
	s_lshl_b32 s1, s1, 6
	s_add_i32 s0, s0, s1
	v_lshrrev_b32_e32 v4, 2, v0
	v_lshlrev_b32_e32 v4, 7, v4
	v_and_b32_e32 v5, 3, v0
	v_lshlrev_b32_e32 v5, 4, v5
	v_add3_u32 v11, v4, v5, s0
	v_lshlrev_b32_e32 v12, 2, v2
	v_lshlrev_b32_e32 v33, 2, v3
	v_lshlrev_b32_e32 v13, 10, v3
	v_lshl_add_u32 v13, v2, 4, v13
	v_bfe_u32 v4, v0, 4, 1
	v_lshlrev_b32_e32 v4, 5, v4
	v_and_b32_e32 v5, 3, v0
	v_lshl_add_u32 v4, v5, 3, v4
	v_bfe_u32 v5, v0, 2, 2
	v_lshl_add_u32 v5, v3, 2, v5
	v_lshl_add_u32 v15, v5, 6, v4
	v_add_u32_e32 v15, 0x8000, v15
	s_lshl_b32 s0, s8, 8
	s_add_i32 s0, s0, 0x18000
	v_lshl_add_u32 v44, v2, 2, s0
	v_lshl_add_u32 v45, v3, 4, s0
	s_lshl_b32 s0, s8, 12
	v_lshl_add_u32 v46, v3, 9, s0
	v_lshl_add_u32 v46, v2, 1, v46
	v_lshl_add_u32 v219, v0, 4, s0
	v_lshrrev_b32_e32 v4, 3, v0
	v_and_b32_e32 v5, 7, v0
	v_lshlrev_b32_e32 v5, 4, v5
	v_lshl_add_u32 v252, v4, 11, v5
	v_lshlrev_b32_e32 v39, 10, v2
	v_lshl_add_u32 v39, v3, 4, v39
	s_lshl_b32 s0, s8, 5
	s_add_i32 s0, s0, s26
	s_lshl_b32 s1, s28, 7
	s_mov_b32 s3, 0
	s_mov_b32 s2, s0
	s_lshl_b64 s[2:3], s[2:3], 11
	s_add_u32 s2, s2, s1
	s_addc_u32 s3, s3, 0
	s_add_u32 s86, s66, s2
	s_addc_u32 s87, s67, s3
	s_mov_b32 s3, 0
	s_mov_b32 s2, s0
	s_lshl_b64 s[2:3], s[2:3], 10
	s_add_u32 s2, s2, s1
	s_addc_u32 s3, s3, 0
	s_add_u32 s84, s42, 0x8200000
	s_addc_u32 s85, s43, 0
	s_add_u32 s84, s84, s2
	s_addc_u32 s85, s85, s3
	s_mov_b32 s3, 0
	s_mov_b32 s2, s30
	s_lshl_b64 s[2:3], s[2:3], 18
	s_add_u32 s80, s56, s2
	s_addc_u32 s81, s57, s3
	s_add_u32 s82, s58, s2
	s_addc_u32 s83, s59, s3
	s_lshl_b32 s0, s30, 6
	s_lshl_b32 s1, s79, 3
	s_add_i32 s0, s0, s1
	s_add_i32 s0, s0, s8
	s_mov_b32 s3, 0
	s_mov_b32 s2, s0
	s_lshl_b64 s[2:3], s[2:3], 13
	s_add_u32 s36, s68, s2
	s_addc_u32 s37, s69, s3
	s_lshl_b32 s22, s8, 5
	s_add_i32 s22, s22, s78
	s_add_i32 s23, s22, 31
	s_lshl_b32 s29, s8, 10
	global_load_dwordx4 v[160:163], v39, s[84:85] offset:0
	global_load_dwordx4 v[164:167], v39, s[84:85] offset:32
	global_load_dwordx4 v[168:171], v39, s[84:85] offset:64
	global_load_dwordx4 v[172:175], v39, s[84:85] offset:96
	s_mov_b32 s95, 0
	s_lshl_b32 s0, s95, 8
	s_add_u32 s2, s36, s0
	s_addc_u32 s3, s37, 0
	global_load_dword v80, v12, s[2:3]
	global_load_dword v81, v12, s[2:3] offset:128
	s_mov_b32 s94, 0
	s_lshl_b32 s0, s94, 13
	s_add_u32 s44, s80, s0
	s_addc_u32 s45, s81, 0
	s_add_u32 s46, s82, s0
	s_addc_u32 s47, s83, 0
	s_and_b32 s1, s94, 3
	s_lshl_b32 s1, s1, 13
	s_add_i32 s1, s1, s29
	s_mov_b32 m0, s1
	s_add_i32 s1, s1, 0x8000
	global_load_lds_dwordx4 v10, s[44:45]
	s_mov_b32 m0, s1
	s_nop 0
	global_load_lds_dwordx4 v11, s[46:47]
	s_mov_b32 s94, 1
	s_lshl_b32 s0, s94, 13
	s_add_u32 s44, s80, s0
	s_addc_u32 s45, s81, 0
	s_add_u32 s46, s82, s0
	s_addc_u32 s47, s83, 0
	s_and_b32 s1, s94, 3
	s_lshl_b32 s1, s1, 13
	s_add_i32 s1, s1, s29
	s_mov_b32 m0, s1
	s_add_i32 s1, s1, 0x8000
	global_load_lds_dwordx4 v10, s[44:45]
	s_mov_b32 m0, s1
	s_nop 0
	global_load_lds_dwordx4 v11, s[46:47]
	s_mov_b32 s94, 2
	s_lshl_b32 s0, s94, 13
	s_add_u32 s44, s80, s0
	s_addc_u32 s45, s81, 0
	s_add_u32 s46, s82, s0
	s_addc_u32 s47, s83, 0
	s_and_b32 s1, s94, 3
	s_lshl_b32 s1, s1, 13
	s_add_i32 s1, s1, s29
	s_mov_b32 m0, s1
	s_add_i32 s1, s1, 0x8000
	global_load_lds_dwordx4 v10, s[44:45]
	s_mov_b32 m0, s1
	s_nop 0
	global_load_lds_dwordx4 v11, s[46:47]
	v_mov_b32_e32 v48, 0
	v_mov_b32_e32 v49, 0
	v_mov_b32_e32 v50, 0
	v_mov_b32_e32 v51, 0
	v_mov_b32_e32 v52, 0
	v_mov_b32_e32 v53, 0
	v_mov_b32_e32 v54, 0
	v_mov_b32_e32 v55, 0
	v_mov_b32_e32 v56, 0
	v_mov_b32_e32 v57, 0
	v_mov_b32_e32 v58, 0
	v_mov_b32_e32 v59, 0
	v_mov_b32_e32 v60, 0
	v_mov_b32_e32 v61, 0
	v_mov_b32_e32 v62, 0
	v_mov_b32_e32 v63, 0
	v_mov_b32_e32 v64, 0
	v_mov_b32_e32 v65, 0
	v_mov_b32_e32 v66, 0
	v_mov_b32_e32 v67, 0
	v_mov_b32_e32 v68, 0
	v_mov_b32_e32 v69, 0
	v_mov_b32_e32 v70, 0
	v_mov_b32_e32 v71, 0
	v_mov_b32_e32 v72, 0
	v_mov_b32_e32 v73, 0
	v_mov_b32_e32 v74, 0
	v_mov_b32_e32 v75, 0
	v_mov_b32_e32 v76, 0
	v_mov_b32_e32 v77, 0
	v_mov_b32_e32 v78, 0
	v_mov_b32_e32 v79, 0
	v_mov_b32_e32 v144, 0
	v_mov_b32_e32 v145, 0
	v_mov_b32_e32 v146, 0
	v_mov_b32_e32 v147, 0
	v_mov_b32_e32 v148, 0
	v_mov_b32_e32 v149, 0
	v_mov_b32_e32 v150, 0
	v_mov_b32_e32 v151, 0
	v_mov_b32_e32 v152, 0
	v_mov_b32_e32 v153, 0
	v_mov_b32_e32 v154, 0
	v_mov_b32_e32 v155, 0
	v_mov_b32_e32 v156, 0
	v_mov_b32_e32 v157, 0
	v_mov_b32_e32 v158, 0
	v_mov_b32_e32 v159, 0
	v_mov_b32_e32 v34, 0
	v_mov_b32_e32 v35, 0
	s_mov_b32 s88, 0
.Lds_loop:
	s_waitcnt vmcnt(2)
	s_barrier
	s_add_i32 s95, s88, 1
	s_add_i32 s0, s89, -1
	s_min_i32 s95, s95, s0
	s_and_b32 s1, s88, 1
	s_cmp_eq_u32 s1, 0
	s_cbranch_scc1 .Lds_ml1
	s_lshl_b32 s0, s95, 8
	s_add_u32 s2, s36, s0
	s_addc_u32 s3, s37, 0
	global_load_dword v80, v12, s[2:3]
	global_load_dword v81, v12, s[2:3] offset:128
	s_branch .Lds_mld
.Lds_ml1:
	s_lshl_b32 s0, s95, 8
	s_add_u32 s2, s36, s0
	s_addc_u32 s3, s37, 0
	global_load_dword v82, v12, s[2:3]
	global_load_dword v83, v12, s[2:3] offset:128
; __device__ __forceinline__ void bmask(f32x16&p0,f32x16&p1,unsigned w0,unsigned w1,int hi){
;   const unsigned m0=w0>>(4*hi), m1=w1>>(4*hi); const unsigned NEGB=0xff800000u;
;   #pragma unroll
;   for(int r=0;r<16;++r){
;     int t0,t1; asm("v_bfe_i32 %0, %1, %2, 1":"=v"(t0):"v"(m0),"n"(cr0(r))); asm("v_bfe_i32 %0, %1, %2, 1":"=v"(t1):"v"(m1),"n"(cr0(r)));
;     asm("v_bfi_b32 %0, %1, %0, %2":"+v"(p0[r]):"v"(t0),"v"(NEGB)); asm("v_bfi_b32 %0, %1, %0, %2":"+v"(p1[r]):"v"(t1),"v"(NEGB)); }
; }
; __device__ __forceinline__ void qkt(f32x16&p0,f32x16&p1,const char*Kslot,const bf16x8*qr,const f32x16&negm,int r32,int hi){
;   const char*kb=Kslot+hi*1024+r32*16;
;   #pragma unroll
;   for(int d0=0;d0<4;++d0){
;     const bf16x8 b0=*reinterpret_cast<const bf16x8*>(kb+d0*2048);
;     const bf16x8 b1=*reinterpret_cast<const bf16x8*>(kb+d0*2048+512);
;     if(d0==0){p0=__builtin_amdgcn_mfma_f32_32x32x16_bf16(b0,qr[0],negm,0,0,0);p1=__builtin_amdgcn_mfma_f32_32x32x16_bf16(b1,qr[0],negm,0,0,0);}
;     else{p0=__builtin_amdgcn_mfma_f32_32x32x16_bf16(b0,qr[d0],p0,0,0,0);p1=__builtin_amdgcn_mfma_f32_32x32x16_bf16(b1,qr[d0],p1,0,0,0);}}
; }
.Lds_mld:
	s_add_i32 s94, s88, 3
	s_add_i32 s0, s89, -1
	s_min_i32 s94, s94, s0
	s_lshl_b32 s0, s94, 13
	s_add_u32 s44, s80, s0
	s_addc_u32 s45, s81, 0
	s_add_u32 s46, s82, s0
	s_addc_u32 s47, s83, 0
	s_and_b32 s1, s94, 3
	s_lshl_b32 s1, s1, 13
	s_add_i32 s1, s1, s29
	s_mov_b32 m0, s1
	s_add_i32 s1, s1, 0x8000
	global_load_lds_dwordx4 v10, s[44:45]
	s_mov_b32 m0, s1
	s_nop 0
	global_load_lds_dwordx4 v11, s[46:47]
	s_lshl_b32 s0, s88, 6
	s_cmp_gt_i32 s0, s23
	s_cbranch_scc1 .Lds_next
	s_and_b32 s0, s88, 3
	s_lshl_b32 s0, s0, 13
	v_add_u32_e32 v14, s0, v13
	ds_read_b128 v[176:179], v14 offset:0
	ds_read_b128 v[180:183], v14 offset:512
	ds_read_b128 v[184:187], v14 offset:2048
	ds_read_b128 v[188:191], v14 offset:2560
	ds_read_b128 v[192:195], v14 offset:4096
	ds_read_b128 v[196:199], v14 offset:4608
	ds_read_b128 v[200:203], v14 offset:6144
	ds_read_b128 v[204:207], v14 offset:6656
	v_add_u32_e32 v32, s0, v15
	s_waitcnt lgkmcnt(6)
	v_mfma_f32_32x32x16_bf16 v[112:127], v[176:179], v[160:163], v[144:159]
	ds_read_b64_tr_b16 v[220:221], v32 offset:0
	ds_read_b64_tr_b16 v[222:223], v32 offset:512
	v_mfma_f32_32x32x16_bf16 v[128:143], v[180:183], v[160:163], v[144:159]
	ds_read_b64_tr_b16 v[224:225], v32 offset:1024
	ds_read_b64_tr_b16 v[226:227], v32 offset:1536
	s_waitcnt lgkmcnt(8)
	v_mfma_f32_32x32x16_bf16 v[112:127], v[184:187], v[164:167], v[112:127]
	ds_read_b64_tr_b16 v[228:229], v32 offset:2048
	ds_read_b64_tr_b16 v[230:231], v32 offset:2560
	v_mfma_f32_32x32x16_bf16 v[128:143], v[188:191], v[164:167], v[128:143]
	ds_read_b64_tr_b16 v[232:233], v32 offset:3072
	ds_read_b64_tr_b16 v[234:235], v32 offset:3584
	s_waitcnt lgkmcnt(10)
	v_mfma_f32_32x32x16_bf16 v[112:127], v[192:195], v[168:171], v[112:127]
	ds_read_b64_tr_b16 v[236:237], v32 offset:4096
	ds_read_b64_tr_b16 v[238:239], v32 offset:4608
	v_mfma_f32_32x32x16_bf16 v[128:143], v[196:199], v[168:171], v[128:143]
	ds_read_b64_tr_b16 v[240:241], v32 offset:5120
	ds_read_b64_tr_b16 v[242:243], v32 offset:5632
	s_waitcnt lgkmcnt(12)
	v_mfma_f32_32x32x16_bf16 v[112:127], v[200:203], v[172:175], v[112:127]
	ds_read_b64_tr_b16 v[244:245], v32 offset:6144
	ds_read_b64_tr_b16 v[246:247], v32 offset:6656
	v_mfma_f32_32x32x16_bf16 v[128:143], v[204:207], v[172:175], v[128:143]
	ds_read_b64_tr_b16 v[248:249], v32 offset:7168
	ds_read_b64_tr_b16 v[250:251], v32 offset:7680
	s_nop 7
	s_nop 1
	s_and_b32 s1, s88, 1
	s_cmp_eq_u32 s1, 0
	s_cbranch_scc1 .Lds_mk0
	v_lshrrev_b32_e32 v4, v33, v82
	v_lshrrev_b32_e32 v5, v33, v83
	v_bfe_i32 v84, v4, 0, 1
	v_bfe_i32 v85, v5, 0, 1
	v_bfe_i32 v86, v4, 1, 1
	v_bfe_i32 v87, v5, 1, 1
	v_bfi_b32 v112, v84, v112, v47
	v_bfi_b32 v128, v85, v128, v47
	v_bfi_b32 v113, v86, v113, v47
	v_bfi_b32 v129, v87, v129, v47
	v_bfe_i32 v84, v4, 2, 1
	v_bfe_i32 v85, v5, 2, 1
	v_bfe_i32 v86, v4, 3, 1
	v_bfe_i32 v87, v5, 3, 1
	v_bfi_b32 v114, v84, v114, v47
	v_bfi_b32 v130, v85, v130, v47
	v_bfi_b32 v115, v86, v115, v47
	v_bfi_b32 v131, v87, v131, v47
	v_bfe_i32 v84, v4, 8, 1
	v_bfe_i32 v85, v5, 8, 1
	v_bfe_i32 v86, v4, 9, 1
	v_bfe_i32 v87, v5, 9, 1
	v_bfi_b32 v116, v84, v116, v47
	v_bfi_b32 v132, v85, v132, v47
	v_bfi_b32 v117, v86, v117, v47
	v_bfi_b32 v133, v87, v133, v47
	v_bfe_i32 v84, v4, 10, 1
	v_bfe_i32 v85, v5, 10, 1
	v_bfe_i32 v86, v4, 11, 1
	v_bfe_i32 v87, v5, 11, 1
	v_bfi_b32 v118, v84, v118, v47
	v_bfi_b32 v134, v85, v134, v47
	v_bfi_b32 v119, v86, v119, v47
	v_bfi_b32 v135, v87, v135, v47
	v_bfe_i32 v84, v4, 16, 1
	v_bfe_i32 v85, v5, 16, 1
	v_bfe_i32 v86, v4, 17, 1
	v_bfe_i32 v87, v5, 17, 1
	v_bfi_b32 v120, v84, v120, v47
	v_bfi_b32 v136, v85, v136, v47
	v_bfi_b32 v121, v86, v121, v47
	v_bfi_b32 v137, v87, v137, v47
	v_bfe_i32 v84, v4, 18, 1
	v_bfe_i32 v85, v5, 18, 1
	v_bfe_i32 v86, v4, 19, 1
	v_bfe_i32 v87, v5, 19, 1
	v_bfi_b32 v122, v84, v122, v47
	v_bfi_b32 v138, v85, v138, v47
	v_bfi_b32 v123, v86, v123, v47
	v_bfi_b32 v139, v87, v139, v47
	v_bfe_i32 v84, v4, 24, 1
	v_bfe_i32 v85, v5, 24, 1
	v_bfe_i32 v86, v4, 25, 1
	v_bfe_i32 v87, v5, 25, 1
	v_bfi_b32 v124, v84, v124, v47
	v_bfi_b32 v140, v85, v140, v47
	v_bfi_b32 v125, v86, v125, v47
	v_bfi_b32 v141, v87, v141, v47
	v_bfe_i32 v84, v4, 26, 1
	v_bfe_i32 v85, v5, 26, 1
	v_bfe_i32 v86, v4, 27, 1
	v_bfe_i32 v87, v5, 27, 1
	v_bfi_b32 v126, v84, v126, v47
	v_bfi_b32 v142, v85, v142, v47
	v_bfi_b32 v127, v86, v127, v47
	v_bfi_b32 v143, v87, v143, v47
	s_branch .Lds_mkd
.Lds_mk0:
	v_lshrrev_b32_e32 v4, v33, v80
	v_lshrrev_b32_e32 v5, v33, v81
	v_bfe_i32 v84, v4, 0, 1
	v_bfe_i32 v85, v5, 0, 1
	v_bfe_i32 v86, v4, 1, 1
	v_bfe_i32 v87, v5, 1, 1
	v_bfi_b32 v112, v84, v112, v47
	v_bfi_b32 v128, v85, v128, v47
	v_bfi_b32 v113, v86, v113, v47
	v_bfi_b32 v129, v87, v129, v47
	v_bfe_i32 v84, v4, 2, 1
	v_bfe_i32 v85, v5, 2, 1
	v_bfe_i32 v86, v4, 3, 1
	v_bfe_i32 v87, v5, 3, 1
	v_bfi_b32 v114, v84, v114, v47
	v_bfi_b32 v130, v85, v130, v47
	v_bfi_b32 v115, v86, v115, v47
	v_bfi_b32 v131, v87, v131, v47
	v_bfe_i32 v84, v4, 8, 1
	v_bfe_i32 v85, v5, 8, 1
	v_bfe_i32 v86, v4, 9, 1
	v_bfe_i32 v87, v5, 9, 1
	v_bfi_b32 v116, v84, v116, v47
	v_bfi_b32 v132, v85, v132, v47
	v_bfi_b32 v117, v86, v117, v47
	v_bfi_b32 v133, v87, v133, v47
	v_bfe_i32 v84, v4, 10, 1
	v_bfe_i32 v85, v5, 10, 1
	v_bfe_i32 v86, v4, 11, 1
	v_bfe_i32 v87, v5, 11, 1
	v_bfi_b32 v118, v84, v118, v47
	v_bfi_b32 v134, v85, v134, v47
	v_bfi_b32 v119, v86, v119, v47
	v_bfi_b32 v135, v87, v135, v47
	v_bfe_i32 v84, v4, 16, 1
	v_bfe_i32 v85, v5, 16, 1
	v_bfe_i32 v86, v4, 17, 1
	v_bfe_i32 v87, v5, 17, 1
	v_bfi_b32 v120, v84, v120, v47
	v_bfi_b32 v136, v85, v136, v47
	v_bfi_b32 v121, v86, v121, v47
	v_bfi_b32 v137, v87, v137, v47
	v_bfe_i32 v84, v4, 18, 1
	v_bfe_i32 v85, v5, 18, 1
	v_bfe_i32 v86, v4, 19, 1
	v_bfe_i32 v87, v5, 19, 1
	v_bfi_b32 v122, v84, v122, v47
	v_bfi_b32 v138, v85, v138, v47
	v_bfi_b32 v123, v86, v123, v47
	v_bfi_b32 v139, v87, v139, v47
	v_bfe_i32 v84, v4, 24, 1
	v_bfe_i32 v85, v5, 24, 1
	v_bfe_i32 v86, v4, 25, 1
	v_bfe_i32 v87, v5, 25, 1
	v_bfi_b32 v124, v84, v124, v47
	v_bfi_b32 v140, v85, v140, v47
	v_bfi_b32 v125, v86, v125, v47
	v_bfi_b32 v141, v87, v141, v47
	v_bfe_i32 v84, v4, 26, 1
	v_bfe_i32 v85, v5, 26, 1
	v_bfe_i32 v86, v4, 27, 1
	v_bfe_i32 v87, v5, 27, 1
	v_bfi_b32 v126, v84, v126, v47
	v_bfi_b32 v142, v85, v142, v47
	v_bfi_b32 v127, v86, v127, v47
	v_bfi_b32 v143, v87, v143, v47

.Lds_norescA:
	v_exp_f32_e32 v112, v112
	v_exp_f32_e32 v113, v113
	v_exp_f32_e32 v114, v114
	v_exp_f32_e32 v115, v115
	v_exp_f32_e32 v116, v116
	v_exp_f32_e32 v117, v117
	v_exp_f32_e32 v118, v118
	v_exp_f32_e32 v119, v119
	v_cvt_pk_bf16_f32 v208, v112, v113
	v_cvt_pk_bf16_f32 v209, v114, v115
	v_cvt_pk_bf16_f32 v210, v116, v117
	v_cvt_pk_bf16_f32 v211, v118, v119
	v_mov_b32_e32 v4, 0
	v_mov_b32_e32 v5, 0
	s_waitcnt lgkmcnt(0)
	v_mfma_f32_32x32x16_bf16 v[48:63], v[208:211], v[220:223], v[48:63]
	v_exp_f32_e32 v120, v120
	v_exp_f32_e32 v121, v121
	v_exp_f32_e32 v122, v122
	v_exp_f32_e32 v123, v123
	v_exp_f32_e32 v124, v124
	v_cvt_pk_bf16_f32 v212, v120, v121
	v_cvt_pk_bf16_f32 v213, v122, v123
	v_add_f32_e32 v4, v112, v4
	v_add_f32_e32 v5, v113, v5
	v_mfma_f32_32x32x16_bf16 v[64:79], v[208:211], v[236:239], v[64:79]
	v_exp_f32_e32 v125, v125
	v_exp_f32_e32 v126, v126
	v_exp_f32_e32 v127, v127
	v_cvt_pk_bf16_f32 v214, v124, v125
	v_cvt_pk_bf16_f32 v215, v126, v127
	v_add_f32_e32 v4, v114, v4
	v_add_f32_e32 v5, v115, v5
	v_add_f32_e32 v4, v116, v4
	v_add_f32_e32 v5, v117, v5
	v_add_f32_e32 v4, v118, v4
	v_add_f32_e32 v5, v119, v5
	v_mfma_f32_32x32x16_bf16 v[48:63], v[212:215], v[224:227], v[48:63]
	v_exp_f32_e32 v128, v128
	v_exp_f32_e32 v129, v129
	v_exp_f32_e32 v130, v130
	v_exp_f32_e32 v131, v131
	v_exp_f32_e32 v132, v132
	v_cvt_pk_bf16_f32 v40, v128, v129
	v_cvt_pk_bf16_f32 v41, v130, v131
	v_add_f32_e32 v4, v120, v4
	v_add_f32_e32 v5, v121, v5
	v_mfma_f32_32x32x16_bf16 v[64:79], v[212:215], v[240:243], v[64:79]
	v_exp_f32_e32 v133, v133
	v_exp_f32_e32 v134, v134
	v_exp_f32_e32 v135, v135
	v_cvt_pk_bf16_f32 v42, v132, v133
	v_cvt_pk_bf16_f32 v43, v134, v135
	v_add_f32_e32 v4, v122, v4
	v_add_f32_e32 v5, v123, v5
	v_add_f32_e32 v4, v124, v4
	v_add_f32_e32 v5, v125, v5
	v_add_f32_e32 v4, v126, v4
	v_add_f32_e32 v5, v127, v5
	v_mfma_f32_32x32x16_bf16 v[48:63], v[40:43], v[228:231], v[48:63]
	v_exp_f32_e32 v136, v136
	v_exp_f32_e32 v137, v137
	v_exp_f32_e32 v138, v138
	v_exp_f32_e32 v139, v139
	v_exp_f32_e32 v140, v140
	v_cvt_pk_bf16_f32 v6, v136, v137
	v_cvt_pk_bf16_f32 v7, v138, v139
	v_add_f32_e32 v4, v128, v4
	v_add_f32_e32 v5, v129, v5
	v_mfma_f32_32x32x16_bf16 v[64:79], v[40:43], v[244:247], v[64:79]
	v_exp_f32_e32 v141, v141
	v_exp_f32_e32 v142, v142
	v_exp_f32_e32 v143, v143
	v_cvt_pk_bf16_f32 v8, v140, v141
	v_cvt_pk_bf16_f32 v9, v142, v143
	v_add_f32_e32 v4, v130, v4
	v_add_f32_e32 v5, v131, v5
	v_add_f32_e32 v4, v132, v4
	v_add_f32_e32 v5, v133, v5
	v_add_f32_e32 v4, v134, v4
	v_add_f32_e32 v5, v135, v5
	v_mfma_f32_32x32x16_bf16 v[48:63], v[6:9], v[232:235], v[48:63]
	v_add_f32_e32 v4, v136, v4
	v_add_f32_e32 v5, v137, v5
	v_mfma_f32_32x32x16_bf16 v[64:79], v[6:9], v[248:251], v[64:79]
	v_add_f32_e32 v4, v138, v4
	v_add_f32_e32 v5, v139, v5
	v_add_f32_e32 v4, v140, v4
	v_add_f32_e32 v5, v141, v5
	v_add_f32_e32 v4, v142, v4
	v_add_f32_e32 v5, v143, v5
	v_add_f32_e32 v4, v4, v5
	v_add_f32_e32 v34, v34, v4
; __device__ __forceinline__ int crow(int r,int hi){return (r&3)+8*(r>>2)+4*hi;}
; __device__ __forceinline__ unsigned cvtpk_s(float lo,float hi){f32x2_t v={lo,hi};bf16x2_t b=__builtin_convertvector(v,bf16x2_t);return __builtin_bit_cast(unsigned,b);}
; #define ATTN_STORE16(p,v) st16_wt((p),(v))
;     ...
;   {auto rr=__builtin_amdgcn_permlane32_swap(__float_as_uint(l_reg),__float_as_uint(l_reg),false,false);l_reg=__uint_as_float(rr[0])+__uint_as_float(rr[1]);}
;   if(hi==0)wsf[32+r32]=l_reg;asm volatile("s_waitcnt lgkmcnt(0)":::"memory");
;   float rli[16];
;   #pragma unroll
;   for(int r=0;r<16;++r)rli[r]=__builtin_amdgcn_rcpf(wsf[32+crow(r,hi)]);
;   bf16*Ow=Ob+(long)(wid*QBLK)*OP;
;   { bf16*stg=(bf16*)(shm+LDS_OST+wid*MWAVE);
;     bf16*stl=stg+bsel*2048+hi*256+r32;
;     if(emode>=2){
;       #pragma unroll
;       for(int r=0;r<16;++r){
;         #pragma unroll
;         for(int d0=0;d0<2;++d0){ const float old=__uint_as_float((unsigned)stl[cr0(r)*64+d0*32]<<16); stl[cr0(r)*64+d0*32]=(bf16)(cvtpk_s(old-lam*(o[d0][r]*rli[r]),0.f)&0xffffu);} }
;     } else {
;       #pragma unroll
;       for(int r=0;r<16;++r){
;         #pragma unroll
;         for(int d0=0;d0<2;++d0)stl[cr0(r)*64+d0*32]=(bf16)(cvtpk_s(o[d0][r]*rli[r],0.f)&0xffffu);}
;     }
;     asm volatile("s_waitcnt lgkmcnt(0)":::"memory");
;     if(emode==0){
;       #pragma unroll
;       for(int i=0;i<4;++i){const int row=i*8+(lane>>3),ch=lane&7; const u32x4 v=*(const u32x4*)(stg+row*64+ch*8); ATTN_STORE16(Ow+(long)row*OP+ch*8,v);}
.Lds_next:
	s_add_i32 s88, s88, 1
	s_cmp_lt_i32 s88, s89
	s_cbranch_scc1 .Lds_loop
	s_waitcnt vmcnt(0)
	s_barrier
	s_nop 7
	s_nop 7
	v_mov_b32_e32 v4, v34
	v_mov_b32_e32 v5, v34
	s_nop 1
	v_permlane32_swap_b32_e32 v4, v5
	v_add_f32_e32 v4, v4, v5
	ds_write_b32 v44, v4 offset:128
	s_waitcnt lgkmcnt(0)
	ds_read_b128 v[112:115], v45 offset:128
	ds_read_b128 v[116:119], v45 offset:160
	ds_read_b128 v[120:123], v45 offset:192
	ds_read_b128 v[124:127], v45 offset:224
	s_waitcnt lgkmcnt(0)
	v_rcp_f32_e32 v112, v112
	v_rcp_f32_e32 v113, v113
	v_rcp_f32_e32 v114, v114
	v_rcp_f32_e32 v115, v115
	v_rcp_f32_e32 v116, v116
	v_rcp_f32_e32 v117, v117
	v_rcp_f32_e32 v118, v118
	v_rcp_f32_e32 v119, v119
	v_rcp_f32_e32 v120, v120
	v_rcp_f32_e32 v121, v121
	v_rcp_f32_e32 v122, v122
	v_rcp_f32_e32 v123, v123
	v_rcp_f32_e32 v124, v124
	v_rcp_f32_e32 v125, v125
	v_rcp_f32_e32 v126, v126
	v_rcp_f32_e32 v127, v127
	s_nop 0
	v_mul_f32_e32 v4, v48, v112
	v_cvt_pk_bf16_f32 v4, v4, v4
	ds_write_b16 v46, v4 offset:0
	v_mul_f32_e32 v4, v49, v113
	v_cvt_pk_bf16_f32 v4, v4, v4
	ds_write_b16 v46, v4 offset:128
	v_mul_f32_e32 v4, v50, v114
	v_cvt_pk_bf16_f32 v4, v4, v4
	ds_write_b16 v46, v4 offset:256
	v_mul_f32_e32 v4, v51, v115
	v_cvt_pk_bf16_f32 v4, v4, v4
	ds_write_b16 v46, v4 offset:384
	v_mul_f32_e32 v4, v52, v116
	v_cvt_pk_bf16_f32 v4, v4, v4
	ds_write_b16 v46, v4 offset:1024
	v_mul_f32_e32 v4, v53, v117
	v_cvt_pk_bf16_f32 v4, v4, v4
	ds_write_b16 v46, v4 offset:1152
	v_mul_f32_e32 v4, v54, v118
	v_cvt_pk_bf16_f32 v4, v4, v4
	ds_write_b16 v46, v4 offset:1280
	v_mul_f32_e32 v4, v55, v119
	v_cvt_pk_bf16_f32 v4, v4, v4
	ds_write_b16 v46, v4 offset:1408
	v_mul_f32_e32 v4, v56, v120
	v_cvt_pk_bf16_f32 v4, v4, v4
	ds_write_b16 v46, v4 offset:2048
	v_mul_f32_e32 v4, v57, v121
	v_cvt_pk_bf16_f32 v4, v4, v4
	ds_write_b16 v46, v4 offset:2176
	v_mul_f32_e32 v4, v58, v122
	v_cvt_pk_bf16_f32 v4, v4, v4
	ds_write_b16 v46, v4 offset:2304
	v_mul_f32_e32 v4, v59, v123
	v_cvt_pk_bf16_f32 v4, v4, v4
	ds_write_b16 v46, v4 offset:2432
	v_mul_f32_e32 v4, v60, v124
	v_cvt_pk_bf16_f32 v4, v4, v4
	ds_write_b16 v46, v4 offset:3072
	v_mul_f32_e32 v4, v61, v125
	v_cvt_pk_bf16_f32 v4, v4, v4
	ds_write_b16 v46, v4 offset:3200
	v_mul_f32_e32 v4, v62, v126
	v_cvt_pk_bf16_f32 v4, v4, v4
	ds_write_b16 v46, v4 offset:3328
	v_mul_f32_e32 v4, v63, v127
	v_cvt_pk_bf16_f32 v4, v4, v4
	ds_write_b16 v46, v4 offset:3456
	v_mul_f32_e32 v4, v64, v112
	v_cvt_pk_bf16_f32 v4, v4, v4
	ds_write_b16 v46, v4 offset:64
	v_mul_f32_e32 v4, v65, v113
	v_cvt_pk_bf16_f32 v4, v4, v4
	ds_write_b16 v46, v4 offset:192
	v_mul_f32_e32 v4, v66, v114
	v_cvt_pk_bf16_f32 v4, v4, v4
	ds_write_b16 v46, v4 offset:320
	v_mul_f32_e32 v4, v67, v115
	v_cvt_pk_bf16_f32 v4, v4, v4
	ds_write_b16 v46, v4 offset:448
	v_mul_f32_e32 v4, v68, v116
	v_cvt_pk_bf16_f32 v4, v4, v4
	ds_write_b16 v46, v4 offset:1088
	v_mul_f32_e32 v4, v69, v117
	v_cvt_pk_bf16_f32 v4, v4, v4
	ds_write_b16 v46, v4 offset:1216
	v_mul_f32_e32 v4, v70, v118
	v_cvt_pk_bf16_f32 v4, v4, v4
	ds_write_b16 v46, v4 offset:1344
	v_mul_f32_e32 v4, v71, v119
	v_cvt_pk_bf16_f32 v4, v4, v4
	ds_write_b16 v46, v4 offset:1472
	v_mul_f32_e32 v4, v72, v120
	v_cvt_pk_bf16_f32 v4, v4, v4
	ds_write_b16 v46, v4 offset:2112
	v_mul_f32_e32 v4, v73, v121
	v_cvt_pk_bf16_f32 v4, v4, v4
	ds_write_b16 v46, v4 offset:2240
	v_mul_f32_e32 v4, v74, v122
	v_cvt_pk_bf16_f32 v4, v4, v4
	ds_write_b16 v46, v4 offset:2368
	v_mul_f32_e32 v4, v75, v123
	v_cvt_pk_bf16_f32 v4, v4, v4
	ds_write_b16 v46, v4 offset:2496
	v_mul_f32_e32 v4, v76, v124
	v_cvt_pk_bf16_f32 v4, v4, v4
	ds_write_b16 v46, v4 offset:3136
	v_mul_f32_e32 v4, v77, v125
	v_cvt_pk_bf16_f32 v4, v4, v4
	ds_write_b16 v46, v4 offset:3264
	v_mul_f32_e32 v4, v78, v126
	v_cvt_pk_bf16_f32 v4, v4, v4
	ds_write_b16 v46, v4 offset:3392
	v_mul_f32_e32 v4, v79, v127
	v_cvt_pk_bf16_f32 v4, v4, v4
	ds_write_b16 v46, v4 offset:3520
	s_waitcnt lgkmcnt(0)
	ds_read_b128 v[176:179], v219 offset:0
	ds_read_b128 v[180:183], v219 offset:1024
	ds_read_b128 v[184:187], v219 offset:2048
	ds_read_b128 v[188:191], v219 offset:3072
	s_waitcnt lgkmcnt(0)
	v_mov_b32_e32 v253, v252
	global_store_dwordx4 v253, v[176:179], s[86:87]
	v_add_u32_e32 v253, 0x4000, v253
	global_store_dwordx4 v253, v[180:183], s[86:87]
	v_add_u32_e32 v253, 0x4000, v253
	global_store_dwordx4 v253, v[184:187], s[86:87]
	v_add_u32_e32 v253, 0x4000, v253
	global_store_dwordx4 v253, v[188:191], s[86:87]
	s_waitcnt vmcnt(0) lgkmcnt(0)
	s_barrier
	s_branch .LBB0_1511
.LBB0_1579:
	s_mov_b32 s79, 3
	s_cbranch_execz .LBB0_1400
	s_branch .LBB0_1401
.LBB0_1583:
	s_cmp_lt_i32 s95, 5
	s_cbranch_scc1 .LBB0_1634
	s_waitcnt vmcnt(0)
	v_readlane_b32 s0, v254, 0
	s_cmp_gt_u32 s0, 63
	s_waitcnt vmcnt(0) lgkmcnt(0)
	s_barrier
	s_cbranch_scc1 .LBB0_1633
	v_mbcnt_lo_u32_b32 v0, -1, 0
	v_mbcnt_hi_u32_b32 v0, -1, v0
	s_nop 0
	v_cmp_eq_u32_e32 vcc, 0, v0
	s_and_saveexec_b64 s[46:47], vcc
	s_cbranch_execz .LBB0_1632
	v_readlane_b32 s0, v254, 8
	s_waitcnt vmcnt(0) expcnt(0) lgkmcnt(0)
	s_nop 0
	v_mov_b32_e32 v0, s0
	ds_read_b32 v2, v0
	ds_read_b32 v0, v0 offset:4
	s_waitcnt lgkmcnt(1)
	v_cmp_ne_u32_e32 vcc, 0, v2
	s_cbranch_vccnz .LBB0_1600
	v_readlane_b32 s2, v254, 3
	v_readlane_b32 s3, v254, 4
	s_load_dwordx2 s[0:1], s[2:3], 0x4
	s_add_u32 s2, s42, 0x4200
	s_addc_u32 s3, s43, 0
	s_add_u32 s4, s42, 0x4400
	s_addc_u32 s5, s43, 0
	s_add_u32 s6, s42, 0x4500
	s_addc_u32 s7, s43, 0
	s_add_u32 s8, s42, 0x4600
	s_addc_u32 s9, s43, 0
	s_add_u32 s10, s42, 0x4700
	s_addc_u32 s11, s43, 0
	s_add_u32 s12, s42, 0x4800
	s_addc_u32 s13, s43, 0
	s_add_u32 s14, s42, 0x4900
	s_addc_u32 s15, s43, 0
	s_add_u32 s16, s42, 0x4a00
	s_addc_u32 s17, s43, 0
	s_add_u32 s18, s42, 0x4b00
	s_addc_u32 s19, s43, 0
	s_add_u32 s20, s42, 0x4c00
	s_addc_u32 s21, s43, 0
	s_add_u32 s22, s42, 0x4d00
	s_addc_u32 s23, s43, 0
	s_add_u32 s24, s42, 0x4e00
	s_addc_u32 s25, s43, 0
	s_add_u32 s26, s42, 0x4f00
	s_addc_u32 s27, s43, 0
	s_add_u32 s30, s42, 0x5000
	s_addc_u32 s31, s43, 0
	s_add_u32 s34, s42, 0x5100
	s_addc_u32 s35, s43, 0
	s_add_u32 s36, s42, 0x5200
	s_addc_u32 s37, s43, 0
	s_waitcnt lgkmcnt(0)
	s_mul_i32 s28, s0, s33
	s_add_u32 s38, s42, 0x5300
	s_mul_i32 s28, s28, s1
	s_addc_u32 s39, s43, 0
	s_mov_b32 s29, 1
	v_mov_b32_e32 v16, 0
	s_branch .LBB0_1589
